# x->residual copy loop widened to 8 grid-stride elements per pass (8 loads in flight per thread), rest as v52
# baseline (speedup 1.0000x reference)
.LBB0_22:
	s_waitcnt lgkmcnt(0)
	s_mov_b64 s[100:101], exec
	v_mov_b32_e32 v182, v0
	v_lshl_add_u64 v[162:163], v[0:1], 4, s[8:9]
	v_lshl_add_u64 v[164:165], s[6:7], 0, v[2:3]
	v_lshl_add_u64 v[162:163], v[162:163], 0, s[16:17]
	v_cmp_gt_i32_e32 vcc, s11, v0
	v_lshl_add_u64 v[166:167], s[4:5], 0, v[2:3]
	s_nop 0
	v_cndmask_b32_e32 v165, v163, v165, vcc
	v_cndmask_b32_e32 v164, v162, v164, vcc
	global_load_dwordx4 v[130:133], v[164:165], off
	v_add_u32_e32 v0, s10, v0
	v_lshl_add_u64 v[2:3], v[2:3], 0, s[12:13]
	v_cmp_ge_i32_e32 vcc, s18, v0
	s_and_b64 exec, exec, vcc
	v_mov_b32_e32 v183, v0
	v_lshl_add_u64 v[162:163], v[0:1], 4, s[8:9]
	v_lshl_add_u64 v[164:165], s[6:7], 0, v[2:3]
	v_lshl_add_u64 v[162:163], v[162:163], 0, s[16:17]
	v_cmp_gt_i32_e32 vcc, s11, v0
	v_lshl_add_u64 v[168:169], s[4:5], 0, v[2:3]
	s_nop 0
	v_cndmask_b32_e32 v165, v163, v165, vcc
	v_cndmask_b32_e32 v164, v162, v164, vcc
	global_load_dwordx4 v[134:137], v[164:165], off
	v_add_u32_e32 v0, s10, v0
	v_lshl_add_u64 v[2:3], v[2:3], 0, s[12:13]
	v_cmp_ge_i32_e32 vcc, s18, v0
	s_and_b64 exec, exec, vcc
	v_mov_b32_e32 v184, v0
	v_lshl_add_u64 v[162:163], v[0:1], 4, s[8:9]
	v_lshl_add_u64 v[164:165], s[6:7], 0, v[2:3]
	v_lshl_add_u64 v[162:163], v[162:163], 0, s[16:17]
	v_cmp_gt_i32_e32 vcc, s11, v0
	v_lshl_add_u64 v[170:171], s[4:5], 0, v[2:3]
	s_nop 0
	v_cndmask_b32_e32 v165, v163, v165, vcc
	v_cndmask_b32_e32 v164, v162, v164, vcc
	global_load_dwordx4 v[138:141], v[164:165], off
	v_add_u32_e32 v0, s10, v0
	v_lshl_add_u64 v[2:3], v[2:3], 0, s[12:13]
	v_cmp_ge_i32_e32 vcc, s18, v0
	s_and_b64 exec, exec, vcc
	v_mov_b32_e32 v185, v0
	v_lshl_add_u64 v[162:163], v[0:1], 4, s[8:9]
	v_lshl_add_u64 v[164:165], s[6:7], 0, v[2:3]
	v_lshl_add_u64 v[162:163], v[162:163], 0, s[16:17]
	v_cmp_gt_i32_e32 vcc, s11, v0
	v_lshl_add_u64 v[172:173], s[4:5], 0, v[2:3]
	s_nop 0
	v_cndmask_b32_e32 v165, v163, v165, vcc
	v_cndmask_b32_e32 v164, v162, v164, vcc
	global_load_dwordx4 v[142:145], v[164:165], off
	v_add_u32_e32 v0, s10, v0
	v_lshl_add_u64 v[2:3], v[2:3], 0, s[12:13]
	v_cmp_ge_i32_e32 vcc, s18, v0
	s_and_b64 exec, exec, vcc
	v_mov_b32_e32 v186, v0
	v_lshl_add_u64 v[162:163], v[0:1], 4, s[8:9]
	v_lshl_add_u64 v[164:165], s[6:7], 0, v[2:3]
	v_lshl_add_u64 v[162:163], v[162:163], 0, s[16:17]
	v_cmp_gt_i32_e32 vcc, s11, v0
	v_lshl_add_u64 v[174:175], s[4:5], 0, v[2:3]
	s_nop 0
	v_cndmask_b32_e32 v165, v163, v165, vcc
	v_cndmask_b32_e32 v164, v162, v164, vcc
	global_load_dwordx4 v[146:149], v[164:165], off
	v_add_u32_e32 v0, s10, v0
	v_lshl_add_u64 v[2:3], v[2:3], 0, s[12:13]
	v_cmp_ge_i32_e32 vcc, s18, v0
	s_and_b64 exec, exec, vcc
	v_mov_b32_e32 v187, v0
	v_lshl_add_u64 v[162:163], v[0:1], 4, s[8:9]
	v_lshl_add_u64 v[164:165], s[6:7], 0, v[2:3]
	v_lshl_add_u64 v[162:163], v[162:163], 0, s[16:17]
	v_cmp_gt_i32_e32 vcc, s11, v0
	v_lshl_add_u64 v[176:177], s[4:5], 0, v[2:3]
	s_nop 0
	v_cndmask_b32_e32 v165, v163, v165, vcc
	v_cndmask_b32_e32 v164, v162, v164, vcc
	global_load_dwordx4 v[150:153], v[164:165], off
	v_add_u32_e32 v0, s10, v0
	v_lshl_add_u64 v[2:3], v[2:3], 0, s[12:13]
	v_cmp_ge_i32_e32 vcc, s18, v0
	s_and_b64 exec, exec, vcc
	v_mov_b32_e32 v188, v0
	v_lshl_add_u64 v[162:163], v[0:1], 4, s[8:9]
	v_lshl_add_u64 v[164:165], s[6:7], 0, v[2:3]
	v_lshl_add_u64 v[162:163], v[162:163], 0, s[16:17]
	v_cmp_gt_i32_e32 vcc, s11, v0
	v_lshl_add_u64 v[178:179], s[4:5], 0, v[2:3]
	s_nop 0
	v_cndmask_b32_e32 v165, v163, v165, vcc
	v_cndmask_b32_e32 v164, v162, v164, vcc
	global_load_dwordx4 v[154:157], v[164:165], off
	v_add_u32_e32 v0, s10, v0
	v_lshl_add_u64 v[2:3], v[2:3], 0, s[12:13]
	v_cmp_ge_i32_e32 vcc, s18, v0
	s_and_b64 exec, exec, vcc
	v_mov_b32_e32 v189, v0
	v_lshl_add_u64 v[162:163], v[0:1], 4, s[8:9]
	v_lshl_add_u64 v[164:165], s[6:7], 0, v[2:3]
	v_lshl_add_u64 v[162:163], v[162:163], 0, s[16:17]
	v_cmp_gt_i32_e32 vcc, s11, v0
	v_lshl_add_u64 v[180:181], s[4:5], 0, v[2:3]
	s_nop 0
	v_cndmask_b32_e32 v165, v163, v165, vcc
	v_cndmask_b32_e32 v164, v162, v164, vcc
	global_load_dwordx4 v[158:161], v[164:165], off
	v_add_u32_e32 v0, s10, v0
	v_lshl_add_u64 v[2:3], v[2:3], 0, s[12:13]
	s_mov_b64 exec, s[100:101]
	v_cmp_ge_i32_e32 vcc, s18, v182
	s_and_b64 exec, exec, vcc
	s_waitcnt vmcnt(7)
	global_store_dwordx4 v[166:167], v[130:133], off
	s_mov_b64 exec, s[100:101]
	v_cmp_ge_i32_e32 vcc, s18, v183
	s_and_b64 exec, exec, vcc
	s_waitcnt vmcnt(7)
	global_store_dwordx4 v[168:169], v[134:137], off
	s_mov_b64 exec, s[100:101]
	v_cmp_ge_i32_e32 vcc, s18, v184
	s_and_b64 exec, exec, vcc
	s_waitcnt vmcnt(7)
	global_store_dwordx4 v[170:171], v[138:141], off
	s_mov_b64 exec, s[100:101]
	v_cmp_ge_i32_e32 vcc, s18, v185
	s_and_b64 exec, exec, vcc
	s_waitcnt vmcnt(7)
	global_store_dwordx4 v[172:173], v[142:145], off
	s_mov_b64 exec, s[100:101]
	v_cmp_ge_i32_e32 vcc, s18, v186
	s_and_b64 exec, exec, vcc
	s_waitcnt vmcnt(7)
	global_store_dwordx4 v[174:175], v[146:149], off
	s_mov_b64 exec, s[100:101]
	v_cmp_ge_i32_e32 vcc, s18, v187
	s_and_b64 exec, exec, vcc
	s_waitcnt vmcnt(7)
	global_store_dwordx4 v[176:177], v[150:153], off
	s_mov_b64 exec, s[100:101]
	v_cmp_ge_i32_e32 vcc, s18, v188
	s_and_b64 exec, exec, vcc
	s_waitcnt vmcnt(7)
	global_store_dwordx4 v[178:179], v[154:157], off
	s_mov_b64 exec, s[100:101]
	v_cmp_ge_i32_e32 vcc, s18, v189
	s_and_b64 exec, exec, vcc
	s_waitcnt vmcnt(7)
	global_store_dwordx4 v[180:181], v[158:161], off
	s_mov_b64 exec, s[100:101]
	v_cmp_lt_i32_e32 vcc, s18, v0
	s_or_b64 s[14:15], vcc, s[14:15]
	s_andn2_b64 exec, exec, s[14:15]
	s_cbranch_execnz .LBB0_22
